# RWKV pass-1 output reduction shortened to 2 DPP levels + 4 partials; GEMM accumulator zeroing with 64-bit moves
# speedup vs baseline: 1.0085x; 1.0085x over previous
; __device__ __forceinline__ float bf2f(bf16_t b) { return __uint_as_float(((unsigned)b) << 16); }
; __device__ __forceinline__ bf16_t f2bf(float f) { unsigned u = __float_as_uint(f); u += 0x7FFFu + ((u >> 16) & 1u); return (bf16_t)(u >> 16); }
; template <int pass>
; __device__ __forceinline__ void rw_item(const Params& p, int l, int seg, int h, LAS float* sm, int tid, int lane, int wave) {
;     ...
;         if (pass == 1) {
;             const int t0 = seg * SEG + sb * TS;
; #pragma unroll
;             for (int rr = 0; rr < 2; ++rr) {
;                 const int t = wave + 8 * rr, tok = t0 + t, c = h * 64 + lane;
;                 const float y = ob[t * 64 + lane];
;                 const float mean = wave_sum(y) * (1.0f / 64.0f);
;                 const float d = y - mean;
;                 const float var = wave_sum(d * d) * (1.0f / 64.0f);
;                 const float yn = d * rsqrtf(var + 64e-5f);
;                 const float val = yn * lnw + lnb + pf_rk[rr] * bf2f(pf_v[rr]);
;                 MX[(size_t)tok * D + c] = f2bf(val * bf2f(pf_g[rr]));
;             }
;         }
.LBB0_454:
	s_mulk_i32 s4, 0xb000
	s_add_i32 s5, s5, s4
	s_waitcnt lgkmcnt(1)
	v_lshl_add_u32 v10, v56, 2, s5
	s_waitcnt lgkmcnt(0)
	s_barrier
	s_and_b32 s0, s30, 1
	s_lshl_b32 s0, s0, 14
	s_add_i32 s0, s0, 0x10000
	v_lshl_add_u32 v10, v56, 2, s0
	s_lshl_b32 s1, s31, 2
	v_add_u32_e32 v11, s1, v10
	ds_read_b32 v104, v11 offset:256
	ds_read_b32 v105, v11 offset:512
	ds_read_b32 v106, v11 offset:768
	ds_read_b32 v11, v11
	s_lshl_b32 s1, s35, 2
	v_add_u32_e32 v10, s1, v10
	ds_read_b32 v107, v10 offset:256
	ds_read_b32 v108, v10 offset:512
	ds_read_b32 v109, v10 offset:768
	ds_read_b32 v12, v10
	v_mov_b32_e32 v13, 0
	s_add_i32 s36, s36, s26
	s_waitcnt lgkmcnt(4)
	v_add_f32_e32 v11, v11, v104
	v_add_f32_e32 v11, v11, v105
	v_add_f32_e32 v11, v11, v106
	s_nop 1
	v_add_f32_dpp v10, v11, v11 quad_perm:[1,0,3,2] row_mask:0xf bank_mask:0xf bound_ctrl:1
	s_add_i32 s4, s36, s59
	s_ashr_i32 s5, s4, 31
	v_add_f32_dpp v10, v10, v10 quad_perm:[2,3,0,1] row_mask:0xf bank_mask:0xf bound_ctrl:1
	s_lshl_b64 s[4:5], s[4:5], 11
	s_add_i32 s30, s30, 1
	v_add_f32_dpp v10, v10, v10 row_half_mirror row_mask:0xf bank_mask:0xf bound_ctrl:1
	s_xor_b64 s[22:23], s[22:23], -1
	s_nop 0
	v_add_f32_dpp v10, v10, v10 row_mirror row_mask:0xf bank_mask:0xf bound_ctrl:1
	s_nop 1
	v_mov_b32_dpp v13, v10 row_bcast:15 row_mask:0xa bank_mask:0xf
	v_add_f32_e32 v10, v10, v13
	v_mov_b32_e32 v13, 0
	s_nop 1
	v_mov_b32_dpp v13, v10 row_bcast:31 row_mask:0xc bank_mask:0xf
	v_add_f32_e32 v10, v10, v13
	v_mov_b32_e32 v13, 0
	v_readlane_b32 s0, v10, 63
	s_nop 1
	v_fmac_f32_e32 v11, s0, v170
	v_mul_f32_e32 v10, v11, v11
	s_nop 1
	v_mov_b32_dpp v10, v10 quad_perm:[1,0,3,2] row_mask:0xf bank_mask:0xf bound_ctrl:1
	v_fmac_f32_e32 v10, v11, v11
	s_nop 1
	v_add_f32_dpp v10, v10, v10 quad_perm:[2,3,0,1] row_mask:0xf bank_mask:0xf bound_ctrl:1
	s_nop 1
	v_add_f32_dpp v10, v10, v10 row_half_mirror row_mask:0xf bank_mask:0xf bound_ctrl:1
	s_nop 1
	v_add_f32_dpp v10, v10, v10 row_mirror row_mask:0xf bank_mask:0xf bound_ctrl:1
	s_nop 1
	v_mov_b32_dpp v13, v10 row_bcast:15 row_mask:0xa bank_mask:0xf
	v_add_f32_e32 v10, v10, v13
	v_mov_b32_e32 v13, 0
	s_nop 1
	v_mov_b32_dpp v13, v10 row_bcast:31 row_mask:0xc bank_mask:0xf
	v_add_f32_e32 v10, v10, v13
	s_nop 0
	v_readlane_b32 s0, v10, 63
	s_nop 1
	v_fma_f32 v10, s0, v168, v160
	v_mul_f32_e32 v13, 0x4b800000, v10
	v_cmp_gt_f32_e64 s[0:1], s68, v10
	s_nop 1
	v_cndmask_b32_e64 v10, v10, v13, s[0:1]
	v_rsq_f32_e32 v10, v10
	s_nop 0
	v_mul_f32_e32 v13, 0x45800000, v10
	v_cndmask_b32_e64 v10, v10, v13, s[0:1]
	v_mul_f32_e32 v10, v11, v10
	v_fma_f32 v10, v55, v10, v57
	s_waitcnt vmcnt(4)
	v_lshlrev_b32_e32 v11, 16, v90
	v_fmac_f32_e32 v10, v89, v11
	s_waitcnt vmcnt(3)
	v_lshlrev_b32_e32 v11, 16, v91
	v_mul_f32_e32 v10, v10, v11
	v_bfe_u32 v11, v10, 16, 1
	v_add3_u32 v13, v10, v11, s61
	s_waitcnt lgkmcnt(0)
	v_add_f32_e32 v12, v12, v107
	v_add_f32_e32 v12, v12, v108
	v_add_f32_e32 v12, v12, v109
	s_nop 1
	v_add_f32_dpp v10, v12, v12 quad_perm:[1,0,3,2] row_mask:0xf bank_mask:0xf bound_ctrl:1
	v_mov_b32_e32 v11, 0
	s_nop 0
	v_add_f32_dpp v10, v10, v10 quad_perm:[2,3,0,1] row_mask:0xf bank_mask:0xf bound_ctrl:1
	s_nop 1
	v_add_f32_dpp v10, v10, v10 row_half_mirror row_mask:0xf bank_mask:0xf bound_ctrl:1
	s_nop 1
	v_add_f32_dpp v10, v10, v10 row_mirror row_mask:0xf bank_mask:0xf bound_ctrl:1
	s_nop 1
	v_mov_b32_dpp v11, v10 row_bcast:15 row_mask:0xa bank_mask:0xf
	v_add_f32_e32 v10, v10, v11
	v_mov_b32_e32 v11, 0
	s_nop 1
	v_mov_b32_dpp v11, v10 row_bcast:31 row_mask:0xc bank_mask:0xf
	v_add_f32_e32 v10, v10, v11
	v_mov_b32_e32 v11, 0
	v_readlane_b32 s0, v10, 63
	s_nop 1
	v_fmac_f32_e32 v12, s0, v170
	v_mul_f32_e32 v10, v12, v12
	s_nop 1
	v_mov_b32_dpp v10, v10 quad_perm:[1,0,3,2] row_mask:0xf bank_mask:0xf bound_ctrl:1
	v_fmac_f32_e32 v10, v12, v12
	s_nop 1
	v_add_f32_dpp v10, v10, v10 quad_perm:[2,3,0,1] row_mask:0xf bank_mask:0xf bound_ctrl:1
	s_nop 1
	v_add_f32_dpp v10, v10, v10 row_half_mirror row_mask:0xf bank_mask:0xf bound_ctrl:1
	s_nop 1
	v_add_f32_dpp v10, v10, v10 row_mirror row_mask:0xf bank_mask:0xf bound_ctrl:1
	s_nop 1
	v_mov_b32_dpp v11, v10 row_bcast:15 row_mask:0xa bank_mask:0xf
	v_add_f32_e32 v10, v10, v11
	v_mov_b32_e32 v11, 0
	s_nop 1
	v_mov_b32_dpp v11, v10 row_bcast:31 row_mask:0xc bank_mask:0xf
	v_add_f32_e32 v10, v10, v11
	s_nop 0
	v_readlane_b32 s0, v10, 63
	s_nop 1
	v_fma_f32 v10, s0, v168, v160
	v_mul_f32_e32 v11, 0x4b800000, v10
	v_cmp_gt_f32_e64 s[0:1], s68, v10
	s_nop 1
	v_cndmask_b32_e64 v10, v10, v11, s[0:1]
	v_rsq_f32_e32 v14, v10
	v_lshl_add_u64 v[10:11], v[64:65], 0, s[4:5]
	global_store_short_d16_hi v[10:11], v13, off
	s_waitcnt vmcnt(2)
	v_lshlrev_b32_e32 v11, 16, v87
	v_mul_f32_e32 v10, 0x45800000, v14
	v_cndmask_b32_e64 v10, v14, v10, s[0:1]
	v_mul_f32_e32 v10, v12, v10
	v_fma_f32 v10, v55, v10, v57
	s_add_i32 s4, s36, s34
	v_fmac_f32_e32 v10, v86, v11
	s_waitcnt vmcnt(1)
	v_lshlrev_b32_e32 v11, 16, v88
	v_mul_f32_e32 v10, v10, v11
	s_ashr_i32 s5, s4, 31
	v_bfe_u32 v11, v10, 16, 1
	s_lshl_b64 s[0:1], s[4:5], 11
	v_add3_u32 v12, v10, v11, s61
	v_lshl_add_u64 v[10:11], v[64:65], 0, s[0:1]
	s_cmp_eq_u32 s30, 8
	global_store_short_d16_hi v[10:11], v12, off
	s_cbranch_scc1 .LBB0_193
	s_cmp_gt_u32 s30, 6
	s_cbranch_scc1 .LBB0_455
	s_add_i32 s0, s30, -1
	s_lshl_b32 s0, s0, 4
	v_add_u32_e32 v14, s0, v81
	v_mad_i64_i32 v[10:11], s[0:1], v14, s60, v[60:61]
	v_lshl_add_u64 v[12:13], v[10:11], 2, s[20:21]
	v_lshlrev_b64 v[10:11], 1, v[10:11]
	global_load_dword v74, v[12:13], off
	v_lshl_add_u64 v[12:13], s[8:9], 0, v[10:11]
	global_load_ushort v76, v[12:13], off
	v_lshl_add_u64 v[12:13], s[18:19], 0, v[10:11]
	global_load_ushort v77, v[12:13], off
	v_lshl_add_u64 v[12:13], s[10:11], 0, v[10:11]
	global_load_ushort v79, v[12:13], off
	v_lshl_add_u64 v[12:13], s[16:17], 0, v[10:11]
	v_lshl_add_u64 v[10:11], s[14:15], 0, v[10:11]
	global_load_ushort v80, v[12:13], off
	global_load_ushort v85, v[10:11], off
	v_add_u32_e32 v10, 8, v14
	v_mad_i64_i32 v[10:11], s[0:1], v10, s60, v[60:61]
	v_lshl_add_u64 v[12:13], v[10:11], 2, s[20:21]
	v_lshlrev_b64 v[10:11], 1, v[10:11]
	global_load_dword v75, v[12:13], off
	v_lshl_add_u64 v[12:13], s[8:9], 0, v[10:11]
	global_load_ushort v246, v[12:13], off
	v_lshl_add_u64 v[12:13], s[18:19], 0, v[10:11]
	global_load_ushort v247, v[12:13], off
	v_lshl_add_u64 v[12:13], s[10:11], 0, v[10:11]
	global_load_ushort v248, v[12:13], off
	v_lshl_add_u64 v[12:13], s[16:17], 0, v[10:11]
	v_lshl_add_u64 v[10:11], s[14:15], 0, v[10:11]
	global_load_ushort v249, v[12:13], off
	global_load_ushort v250, v[10:11], off
; #define LAS __attribute__((address_space(3)))
; template <int pass>
; __device__ __forceinline__ void rw_item(const Params& p, int l, int seg, int h, LAS float* sm, int tid, int lane, int wave) {
;     ...
;         float pf_rk[2] = {0.f, 0.f}; bf16_t pf_v[2] = {0, 0}, pf_g[2] = {0, 0};
;         if (pass == 1) {
; #pragma unroll
;             for (int rr = 0; rr < 2; ++rr) { const int tok = seg * SEG + sb * TS + wave + 8 * rr; const size_t g = (size_t)tok * RWW + h * 64 + lane; pf_rk[rr] = RK[(size_t)tok * 8 + h]; pf_v[rr] = Vv[g]; pf_g[rr] = Gg[g]; }
;         }
;         f32x4 nw4 = *(const LAS f32x4*)(bf + 1024 + kq * 4), nk4 = *(const LAS f32x4*)(bf + 2048 + kq * 4);
;         f32x4 na4 = *(const LAS f32x4*)(bf + 3072 + kq * 4), nb4 = *(const LAS f32x4*)(bf + 4096 + kq * 4);
;         f32x2 nvv = *(const LAS f32x2*)(bf + 5120 + j0);
;         f32x4 nq4 = (pass == 1) ? *(const LAS f32x4*)(bf + kq * 4) : (f32x4){0.f, 0.f, 0.f, 0.f};
; #pragma unroll 8
.LBB0_455:
	s_lshl_b32 s36, s30, 4
	s_add_i32 s0, s27, s36
	s_ashr_i32 s1, s0, 31
	v_mad_i64_i32 v[10:11], s[38:39], s0, v169, v[62:63]
	s_and_b32 s4, s30, 1
	s_lshl_b64 s[38:39], s[0:1], 5
	s_add_u32 s38, s28, s38
	s_addc_u32 s39, s29, s39
	v_lshlrev_b64 v[10:11], 1, v[10:11]
	s_add_i32 s0, s0, 8
	v_lshl_add_u64 v[12:13], s[16:17], 0, v[10:11]
	v_lshl_add_u64 v[10:11], s[12:13], 0, v[10:11]
	s_ashr_i32 s1, s0, 31
	global_load_dword v89, v1, s[38:39]
	global_load_ushort v90, v[12:13], off
	global_load_ushort v91, v[10:11], off
	v_mad_i64_i32 v[10:11], s[38:39], s0, v169, v[62:63]
	s_lshl_b64 s[0:1], s[0:1], 5
	s_add_u32 s0, s28, s0
	v_lshlrev_b64 v[10:11], 1, v[10:11]
	s_addc_u32 s1, s29, s1
	v_lshl_add_u64 v[12:13], s[16:17], 0, v[10:11]
	v_lshl_add_u64 v[10:11], s[12:13], 0, v[10:11]
	global_load_dword v86, v1, s[0:1]
	global_load_ushort v87, v[12:13], off
	global_load_ushort v88, v[10:11], off
	s_mul_i32 s0, s4, 0x6000
	s_add_i32 s5, s0, 0
	v_lshl_add_u32 v22, v0, 2, s5
	ds_read_b128 v[10:13], v22 offset:4096
	ds_read_b128 v[14:17], v22 offset:8192
	ds_read_b128 v[18:21], v22 offset:12288
	ds_read_b128 v[26:29], v22 offset:16384
	v_lshl_add_u32 v93, v58, 2, s5
	ds_read_b64 v[50:51], v93 offset:20480
	ds_read_b128 v[22:25], v22
	v_cndmask_b32_e64 v30, 0, 1, s[22:23]
	v_mul_lo_u32 v31, v30, s54
	v_add_u32_e32 v92, v82, v31
	v_add_u32_e32 v94, v83, v31
	v_lshrrev_b32_e32 v95, 4, v54
	v_bfe_u32 v103, v54, 2, 2
	v_lshlrev_b32_e32 v95, 3, v95
	v_lshl_add_u32 v95, v103, 8, v95
	v_lshl_add_u32 v95, v30, 14, v95
	v_add_u32_e32 v95, 0x10000, v95
	v_and_b32_e32 v103, 3, v54
	v_cmp_eq_u32_e32 vcc, 0, v103
	s_movk_i32 s37, 0x200
	s_mov_b32 s38, 0
	s_branch .LBB0_457

; #define LAS __attribute__((address_space(3)))
; template <int pass>
; __device__ __forceinline__ void rw_item(const Params& p, int l, int seg, int h, LAS float* sm, int tid, int lane, int wave) {
;     ...
;         for (int t = 0; t < TS; ++t) {
;             const f32x4 w4 = nw4, k4 = nk4, a4 = na4, b4 = nb4, q4 = nq4; const f32x2 vv = nvv;
;             {
;                 const int tn = (t + 1 < TS) ? t + 1 : t, on = tn * 64 + kq * 4;
;                 nw4 = *(const LAS f32x4*)(bf + 1024 + on); nk4 = *(const LAS f32x4*)(bf + 2048 + on);
;                 na4 = *(const LAS f32x4*)(bf + 3072 + on); nb4 = *(const LAS f32x4*)(bf + 4096 + on);
;                 nvv = *(const LAS f32x2*)(bf + 5120 + tn * 64 + j0);
;                 if (pass == 1) nq4 = *(const LAS f32x4*)(bf + on);
;             }
;             const f32x2 vA = {vv.x, vv.x}, vB = {vv.y, vv.y};
;             f32x2 ua = b4.xy * sA[0], ub = b4.xy * sB[0];
;             ua = b4.zw * sA[1] + ua; ub = b4.zw * sB[1] + ub;
;             float uA = ua.x + ua.y, uB = ub.x + ub.y, gA = 0.f, gB = 0.f;
;             if (pass == 0) {
;                 f32x2 qa = b4.xy * pA[0], qb = b4.xy * pB[0];
;                 qa = b4.zw * pA[1] + qa; qb = b4.zw * pB[1] + qb;
;                 gA = qa.x + qa.y; gB = qb.x + qb.y;
;                 kq_sum16x4(uA, uB, gA, gB);
;             } else { uA = kq_sum<16>(uA); uB = kq_sum<16>(uB); }
;             const f32x2 uA2 = {uA, uA}, uB2 = {uB, uB};
;             { const f32x2 t0_ = k4.xy * vA - a4.xy * uA2, t1_ = k4.zw * vA - a4.zw * uA2; sA[0] = w4.xy * sA[0] + t0_; sA[1] = w4.zw * sA[1] + t1_; }
;             { const f32x2 t0_ = k4.xy * vB - a4.xy * uB2, t1_ = k4.zw * vB - a4.zw * uB2; sB[0] = w4.xy * sB[0] + t0_; sB[1] = w4.zw * sB[1] + t1_; }
;             if (pass == 0) {
;                 const f32x2 gA2 = {gA, gA}, gB2 = {gB, gB};
;                 pA[0] = w4.xy * pA[0] - a4.xy * gA2; pA[1] = w4.zw * pA[1] - a4.zw * gA2;
;                 pB[0] = w4.xy * pB[0] - a4.xy * gB2; pB[1] = w4.zw * pB[1] - a4.zw * gB2;
;             } else {
;                 f32x2 oa = q4.xy * sA[0], ob2 = q4.xy * sB[0];
;                 oa = q4.zw * sA[1] + oa; ob2 = q4.zw * sB[1] + ob2;
;                 const float oA = kq_sum<16>(oa.x + oa.y), oB = kq_sum<16>(ob2.x + ob2.y);
;                 if (kq == 0) *(LAS f32x2*)(ob + t * 64 + j0) = (f32x2){oA, oB};
;             }
;         }
.LBB0_457:
	s_waitcnt lgkmcnt(2)
	v_pk_mul_f32 v[52:53], v[28:29], v[8:9]
	v_pk_mul_f32 v[28:29], v[28:29], v[4:5]
	v_pk_fma_f32 v[52:53], v[26:27], v[6:7], v[52:53]
	v_pk_fma_f32 v[26:27], v[26:27], v[2:3], v[28:29]
	v_add_f32_e32 v28, v52, v53
	v_add_f32_e32 v27, v26, v27
	v_add_u32_e32 v97, s38, v94
	v_add_f32_dpp v26, v28, v28 quad_perm:[1,0,3,2] row_mask:0xf bank_mask:0xf bound_ctrl:1
	v_add_f32_dpp v27, v27, v27 quad_perm:[1,0,3,2] row_mask:0xf bank_mask:0xf bound_ctrl:1
	ds_read_b128 v[34:37], v97 offset:8192
	ds_read_b128 v[38:41], v97 offset:12288
	v_add_f32_dpp v26, v26, v26 quad_perm:[2,3,0,1] row_mask:0xf bank_mask:0xf bound_ctrl:1
	v_add_f32_dpp v27, v27, v27 quad_perm:[2,3,0,1] row_mask:0xf bank_mask:0xf bound_ctrl:1
	v_add_u32_e32 v98, s38, v92
	v_add_f32_dpp v26, v26, v26 row_half_mirror row_mask:0xf bank_mask:0xf bound_ctrl:1
	v_add_f32_dpp v27, v27, v27 row_half_mirror row_mask:0xf bank_mask:0xf bound_ctrl:1
	ds_read_b128 v[46:49], v97 offset:16384
	ds_read_b64 v[66:67], v98
	ds_read_b128 v[42:45], v97 offset:4096
	ds_read_b128 v[30:33], v97
	v_add_f32_dpp v26, v26, v26 row_mirror row_mask:0xf bank_mask:0xf bound_ctrl:1
	v_add_f32_dpp v28, v27, v27 row_mirror row_mask:0xf bank_mask:0xf bound_ctrl:1
	v_pk_mul_f32 v[52:53], v[18:19], v[26:27] op_sel_hi:[1,0]
	v_pk_mul_f32 v[18:19], v[18:19], v[28:29] op_sel_hi:[1,0]
	s_waitcnt lgkmcnt(7)
	v_pk_fma_f32 v[52:53], v[14:15], v[50:51], v[52:53] op_sel_hi:[1,0,1] neg_lo:[0,0,1] neg_hi:[0,0,1]
	v_pk_mul_f32 v[26:27], v[20:21], v[26:27] op_sel_hi:[1,0]
	v_pk_fma_f32 v[14:15], v[14:15], v[50:51], v[18:19] op_sel:[0,1,0] neg_lo:[0,0,1] neg_hi:[0,0,1]
	v_pk_mul_f32 v[18:19], v[20:21], v[28:29] op_sel_hi:[1,0]
	v_pk_fma_f32 v[26:27], v[16:17], v[50:51], v[26:27] op_sel_hi:[1,0,1] neg_lo:[0,0,1] neg_hi:[0,0,1]
	v_pk_fma_f32 v[6:7], v[10:11], v[6:7], v[52:53]
	v_pk_fma_f32 v[16:17], v[16:17], v[50:51], v[18:19] op_sel:[0,1,0] neg_lo:[0,0,1] neg_hi:[0,0,1]
	v_pk_fma_f32 v[14:15], v[10:11], v[2:3], v[14:15]
	v_pk_fma_f32 v[8:9], v[12:13], v[8:9], v[26:27]
	v_pk_fma_f32 v[16:17], v[12:13], v[4:5], v[16:17]
	s_waitcnt lgkmcnt(6)
	v_pk_mul_f32 v[2:3], v[22:23], v[6:7]
	v_pk_mul_f32 v[4:5], v[22:23], v[14:15]
	v_pk_fma_f32 v[2:3], v[24:25], v[8:9], v[2:3]
	v_pk_fma_f32 v[4:5], v[24:25], v[16:17], v[4:5]
	v_add_f32_e32 v100, v2, v3
	v_add_f32_e32 v101, v4, v5
	v_lshl_add_u32 v96, s38, 2, v95
	s_waitcnt lgkmcnt(2)
	v_pk_mul_f32 v[26:27], v[48:49], v[8:9]
	v_pk_mul_f32 v[28:29], v[48:49], v[16:17]
	v_pk_fma_f32 v[26:27], v[46:47], v[6:7], v[26:27]
	v_pk_fma_f32 v[28:29], v[46:47], v[14:15], v[28:29]
	v_add_f32_e32 v26, v26, v27
	v_add_f32_e32 v27, v28, v29
	ds_read_b128 v[10:13], v97 offset:8448
	ds_read_b128 v[22:25], v97 offset:12544
	ds_read_b128 v[50:53], v97 offset:16640
	ds_read_b64 v[68:69], v98 offset:256
	ds_read_b128 v[18:21], v97 offset:4352
	ds_read_b128 v[2:5], v97 offset:256
	v_add_f32_dpp v26, v26, v26 quad_perm:[1,0,3,2] row_mask:0xf bank_mask:0xf bound_ctrl:1
	v_add_f32_dpp v27, v27, v27 quad_perm:[1,0,3,2] row_mask:0xf bank_mask:0xf bound_ctrl:1
	v_add_f32_dpp v100, v100, v100 quad_perm:[1,0,3,2] row_mask:0xf bank_mask:0xf bound_ctrl:1
	v_add_f32_dpp v101, v101, v101 quad_perm:[1,0,3,2] row_mask:0xf bank_mask:0xf bound_ctrl:1
	v_add_f32_dpp v26, v26, v26 quad_perm:[2,3,0,1] row_mask:0xf bank_mask:0xf bound_ctrl:1
	v_add_f32_dpp v27, v27, v27 quad_perm:[2,3,0,1] row_mask:0xf bank_mask:0xf bound_ctrl:1
	v_add_f32_dpp v100, v100, v100 quad_perm:[2,3,0,1] row_mask:0xf bank_mask:0xf bound_ctrl:1
	v_add_f32_dpp v101, v101, v101 quad_perm:[2,3,0,1] row_mask:0xf bank_mask:0xf bound_ctrl:1
	v_add_f32_dpp v26, v26, v26 row_half_mirror row_mask:0xf bank_mask:0xf bound_ctrl:1
	v_add_f32_dpp v27, v27, v27 row_half_mirror row_mask:0xf bank_mask:0xf bound_ctrl:1
	s_nop 0
	v_add_f32_dpp v26, v26, v26 row_mirror row_mask:0xf bank_mask:0xf bound_ctrl:1
	v_pk_mul_f32 v[46:47], v[38:39], v[26:27] op_sel_hi:[1,0]
	v_add_f32_dpp v28, v27, v27 row_mirror row_mask:0xf bank_mask:0xf bound_ctrl:1
	s_mov_b64 exec, vcc
	ds_write_b64 v96, v[100:101]
	s_mov_b64 exec, -1
	s_waitcnt lgkmcnt(8)
	v_pk_fma_f32 v[46:47], v[34:35], v[66:67], v[46:47] op_sel_hi:[1,0,1] neg_lo:[0,0,1] neg_hi:[0,0,1]
	v_pk_mul_f32 v[26:27], v[40:41], v[26:27] op_sel_hi:[1,0]
	s_waitcnt lgkmcnt(7)
	v_pk_fma_f32 v[46:47], v[42:43], v[6:7], v[46:47]
	v_pk_fma_f32 v[26:27], v[36:37], v[66:67], v[26:27] op_sel_hi:[1,0,1] neg_lo:[0,0,1] neg_hi:[0,0,1]
	v_pk_mul_f32 v[6:7], v[38:39], v[28:29] op_sel_hi:[1,0]
	v_pk_fma_f32 v[48:49], v[44:45], v[8:9], v[26:27]
	v_pk_fma_f32 v[6:7], v[34:35], v[66:67], v[6:7] op_sel:[0,1,0] neg_lo:[0,0,1] neg_hi:[0,0,1]
	v_pk_mul_f32 v[8:9], v[40:41], v[28:29] op_sel_hi:[1,0]
	v_pk_fma_f32 v[38:39], v[42:43], v[14:15], v[6:7]
	v_pk_fma_f32 v[8:9], v[36:37], v[66:67], v[8:9] op_sel:[0,1,0] neg_lo:[0,0,1] neg_hi:[0,0,1]
	s_waitcnt lgkmcnt(7)
	v_pk_mul_f32 v[6:7], v[30:31], v[46:47]
	v_pk_fma_f32 v[40:41], v[44:45], v[16:17], v[8:9]
	v_pk_mul_f32 v[8:9], v[30:31], v[38:39]
	v_pk_fma_f32 v[6:7], v[32:33], v[48:49], v[6:7]
	v_pk_fma_f32 v[8:9], v[32:33], v[40:41], v[8:9]
	v_add_f32_e32 v100, v6, v7
	v_add_f32_e32 v101, v8, v9
	s_waitcnt lgkmcnt(3)
; #define LAS __attribute__((address_space(3)))
; template <int pass>
; __device__ __forceinline__ void rw_item(const Params& p, int l, int seg, int h, LAS float* sm, int tid, int lane, int wave) {
;     ...
;         for (int t = 0; t < TS; ++t) {
;             const f32x4 w4 = nw4, k4 = nk4, a4 = na4, b4 = nb4, q4 = nq4; const f32x2 vv = nvv;
;             {
;                 const int tn = (t + 1 < TS) ? t + 1 : t, on = tn * 64 + kq * 4;
;                 nw4 = *(const LAS f32x4*)(bf + 1024 + on); nk4 = *(const LAS f32x4*)(bf + 2048 + on);
;                 na4 = *(const LAS f32x4*)(bf + 3072 + on); nb4 = *(const LAS f32x4*)(bf + 4096 + on);
;                 nvv = *(const LAS f32x2*)(bf + 5120 + tn * 64 + j0);
;                 if (pass == 1) nq4 = *(const LAS f32x4*)(bf + on);
;             }
;             const f32x2 vA = {vv.x, vv.x}, vB = {vv.y, vv.y};
;             f32x2 ua = b4.xy * sA[0], ub = b4.xy * sB[0];
;             ua = b4.zw * sA[1] + ua; ub = b4.zw * sB[1] + ub;
;             float uA = ua.x + ua.y, uB = ub.x + ub.y, gA = 0.f, gB = 0.f;
;             if (pass == 0) {
;                 f32x2 qa = b4.xy * pA[0], qb = b4.xy * pB[0];
;                 qa = b4.zw * pA[1] + qa; qb = b4.zw * pB[1] + qb;
;                 gA = qa.x + qa.y; gB = qb.x + qb.y;
;                 kq_sum16x4(uA, uB, gA, gB);
;             } else { uA = kq_sum<16>(uA); uB = kq_sum<16>(uB); }
;             const f32x2 uA2 = {uA, uA}, uB2 = {uB, uB};
;             { const f32x2 t0_ = k4.xy * vA - a4.xy * uA2, t1_ = k4.zw * vA - a4.zw * uA2; sA[0] = w4.xy * sA[0] + t0_; sA[1] = w4.zw * sA[1] + t1_; }
;             { const f32x2 t0_ = k4.xy * vB - a4.xy * uB2, t1_ = k4.zw * vB - a4.zw * uB2; sB[0] = w4.xy * sB[0] + t0_; sB[1] = w4.zw * sB[1] + t1_; }
;             if (pass == 0) {
;                 const f32x2 gA2 = {gA, gA}, gB2 = {gB, gB};
;                 pA[0] = w4.xy * pA[0] - a4.xy * gA2; pA[1] = w4.zw * pA[1] - a4.zw * gA2;
;                 pB[0] = w4.xy * pB[0] - a4.xy * gB2; pB[1] = w4.zw * pB[1] - a4.zw * gB2;
;             } else {
;                 f32x2 oa = q4.xy * sA[0], ob2 = q4.xy * sB[0];
;                 oa = q4.zw * sA[1] + oa; ob2 = q4.zw * sB[1] + ob2;
;                 const float oA = kq_sum<16>(oa.x + oa.y), oB = kq_sum<16>(ob2.x + ob2.y);
;                 if (kq == 0) *(LAS f32x2*)(ob + t * 64 + j0) = (f32x2){oA, oB};
;             }
;         }
	v_pk_mul_f32 v[44:45], v[52:53], v[48:49]
	v_pk_mul_f32 v[52:53], v[52:53], v[40:41]
	v_pk_fma_f32 v[44:45], v[50:51], v[46:47], v[44:45]
	v_pk_fma_f32 v[50:51], v[50:51], v[38:39], v[52:53]
	v_add_f32_e32 v44, v44, v45
	v_add_f32_e32 v45, v50, v51
	ds_read_b128 v[14:17], v97 offset:8704
	ds_read_b128 v[30:33], v97 offset:12800
	ds_read_b128 v[34:37], v97 offset:16896
	ds_read_b64 v[42:43], v98 offset:512
	ds_read_b128 v[26:29], v97 offset:4608
	ds_read_b128 v[6:9], v97 offset:512
	v_add_f32_dpp v44, v44, v44 quad_perm:[1,0,3,2] row_mask:0xf bank_mask:0xf bound_ctrl:1
	v_add_f32_dpp v45, v45, v45 quad_perm:[1,0,3,2] row_mask:0xf bank_mask:0xf bound_ctrl:1
	v_add_f32_dpp v100, v100, v100 quad_perm:[1,0,3,2] row_mask:0xf bank_mask:0xf bound_ctrl:1
	v_add_f32_dpp v101, v101, v101 quad_perm:[1,0,3,2] row_mask:0xf bank_mask:0xf bound_ctrl:1
	v_add_f32_dpp v44, v44, v44 quad_perm:[2,3,0,1] row_mask:0xf bank_mask:0xf bound_ctrl:1
	v_add_f32_dpp v45, v45, v45 quad_perm:[2,3,0,1] row_mask:0xf bank_mask:0xf bound_ctrl:1
	v_add_f32_dpp v100, v100, v100 quad_perm:[2,3,0,1] row_mask:0xf bank_mask:0xf bound_ctrl:1
	v_add_f32_dpp v101, v101, v101 quad_perm:[2,3,0,1] row_mask:0xf bank_mask:0xf bound_ctrl:1
	v_add_f32_dpp v44, v44, v44 row_half_mirror row_mask:0xf bank_mask:0xf bound_ctrl:1
	v_add_f32_dpp v45, v45, v45 row_half_mirror row_mask:0xf bank_mask:0xf bound_ctrl:1
	s_nop 0
	v_add_f32_dpp v44, v44, v44 row_mirror row_mask:0xf bank_mask:0xf bound_ctrl:1
	v_add_f32_dpp v50, v45, v45 row_mirror row_mask:0xf bank_mask:0xf bound_ctrl:1
	s_mov_b64 exec, vcc
	ds_write_b64 v96, v[100:101] offset:1024
	s_mov_b64 exec, -1
	v_pk_mul_f32 v[52:53], v[22:23], v[44:45] op_sel_hi:[1,0]
	v_pk_mul_f32 v[22:23], v[22:23], v[50:51] op_sel_hi:[1,0]
	s_waitcnt lgkmcnt(9)
	v_pk_fma_f32 v[52:53], v[10:11], v[68:69], v[52:53] op_sel_hi:[1,0,1] neg_lo:[0,0,1] neg_hi:[0,0,1]
	v_pk_mul_f32 v[44:45], v[24:25], v[44:45] op_sel_hi:[1,0]
	v_pk_fma_f32 v[10:11], v[10:11], v[68:69], v[22:23] op_sel:[0,1,0] neg_lo:[0,0,1] neg_hi:[0,0,1]
	v_pk_mul_f32 v[22:23], v[24:25], v[50:51] op_sel_hi:[1,0]
	v_pk_fma_f32 v[44:45], v[12:13], v[68:69], v[44:45] op_sel_hi:[1,0,1] neg_lo:[0,0,1] neg_hi:[0,0,1]
	s_waitcnt lgkmcnt(8)
	v_pk_fma_f32 v[46:47], v[18:19], v[46:47], v[52:53]
	v_pk_fma_f32 v[12:13], v[12:13], v[68:69], v[22:23] op_sel:[0,1,0] neg_lo:[0,0,1] neg_hi:[0,0,1]
	v_pk_fma_f32 v[50:51], v[18:19], v[38:39], v[10:11]
	v_pk_fma_f32 v[48:49], v[20:21], v[48:49], v[44:45]
	v_pk_fma_f32 v[52:53], v[20:21], v[40:41], v[12:13]
	s_waitcnt lgkmcnt(8)
	v_pk_mul_f32 v[10:11], v[2:3], v[46:47]
	v_pk_mul_f32 v[2:3], v[2:3], v[50:51]
	v_pk_fma_f32 v[10:11], v[4:5], v[48:49], v[10:11]
	v_pk_fma_f32 v[2:3], v[4:5], v[52:53], v[2:3]
	v_add_f32_e32 v101, v2, v3
	v_add_f32_e32 v100, v10, v11
	s_waitcnt lgkmcnt(3)
	v_pk_mul_f32 v[66:67], v[36:37], v[48:49]
	v_pk_mul_f32 v[36:37], v[36:37], v[52:53]
	v_pk_fma_f32 v[66:67], v[34:35], v[46:47], v[66:67]
	v_pk_fma_f32 v[34:35], v[34:35], v[50:51], v[36:37]
	v_add_f32_e32 v36, v66, v67
	v_add_f32_e32 v35, v34, v35
	ds_read_b128 v[10:13], v97 offset:8960
	ds_read_b128 v[22:25], v97 offset:13056
	ds_read_b128 v[38:41], v97 offset:17152
	ds_read_b64 v[44:45], v98 offset:768
	ds_read_b128 v[18:21], v97 offset:4864
	ds_read_b128 v[2:5], v97 offset:768
	v_add_f32_dpp v34, v36, v36 quad_perm:[1,0,3,2] row_mask:0xf bank_mask:0xf bound_ctrl:1
	v_add_f32_dpp v35, v35, v35 quad_perm:[1,0,3,2] row_mask:0xf bank_mask:0xf bound_ctrl:1
	v_add_f32_dpp v100, v100, v100 quad_perm:[1,0,3,2] row_mask:0xf bank_mask:0xf bound_ctrl:1
	v_add_f32_dpp v101, v101, v101 quad_perm:[1,0,3,2] row_mask:0xf bank_mask:0xf bound_ctrl:1
	v_add_f32_dpp v34, v34, v34 quad_perm:[2,3,0,1] row_mask:0xf bank_mask:0xf bound_ctrl:1
	v_add_f32_dpp v35, v35, v35 quad_perm:[2,3,0,1] row_mask:0xf bank_mask:0xf bound_ctrl:1
	v_add_f32_dpp v100, v100, v100 quad_perm:[2,3,0,1] row_mask:0xf bank_mask:0xf bound_ctrl:1
	v_add_f32_dpp v101, v101, v101 quad_perm:[2,3,0,1] row_mask:0xf bank_mask:0xf bound_ctrl:1
	v_add_f32_dpp v34, v34, v34 row_half_mirror row_mask:0xf bank_mask:0xf bound_ctrl:1
	v_add_f32_dpp v35, v35, v35 row_half_mirror row_mask:0xf bank_mask:0xf bound_ctrl:1
	s_nop 0
	v_add_f32_dpp v34, v34, v34 row_mirror row_mask:0xf bank_mask:0xf bound_ctrl:1
	v_add_f32_dpp v36, v35, v35 row_mirror row_mask:0xf bank_mask:0xf bound_ctrl:1
	s_mov_b64 exec, vcc
	ds_write_b64 v96, v[100:101] offset:2048
	s_mov_b64 exec, -1
	v_pk_mul_f32 v[66:67], v[30:31], v[34:35] op_sel_hi:[1,0]
	v_pk_mul_f32 v[30:31], v[30:31], v[36:37] op_sel_hi:[1,0]
	s_waitcnt lgkmcnt(9)
	v_pk_fma_f32 v[66:67], v[14:15], v[42:43], v[66:67] op_sel_hi:[1,0,1] neg_lo:[0,0,1] neg_hi:[0,0,1]
	v_pk_mul_f32 v[34:35], v[32:33], v[34:35] op_sel_hi:[1,0]
	v_pk_fma_f32 v[14:15], v[14:15], v[42:43], v[30:31] op_sel:[0,1,0] neg_lo:[0,0,1] neg_hi:[0,0,1]
	v_pk_mul_f32 v[30:31], v[32:33], v[36:37] op_sel_hi:[1,0]
	v_pk_fma_f32 v[34:35], v[16:17], v[42:43], v[34:35] op_sel_hi:[1,0,1] neg_lo:[0,0,1] neg_hi:[0,0,1]
	s_waitcnt lgkmcnt(8)
	v_pk_fma_f32 v[46:47], v[26:27], v[46:47], v[66:67]
	v_pk_fma_f32 v[16:17], v[16:17], v[42:43], v[30:31] op_sel:[0,1,0] neg_lo:[0,0,1] neg_hi:[0,0,1]
	v_pk_fma_f32 v[42:43], v[26:27], v[50:51], v[14:15]
	v_pk_fma_f32 v[48:49], v[28:29], v[48:49], v[34:35]
	v_pk_fma_f32 v[52:53], v[28:29], v[52:53], v[16:17]
	s_waitcnt lgkmcnt(8)
	v_pk_mul_f32 v[14:15], v[6:7], v[46:47]
	v_pk_mul_f32 v[6:7], v[6:7], v[42:43]
	v_pk_fma_f32 v[14:15], v[8:9], v[48:49], v[14:15]
	v_pk_fma_f32 v[6:7], v[8:9], v[52:53], v[6:7]
	v_add_f32_e32 v101, v6, v7
	v_add_f32_e32 v100, v14, v15
	s_waitcnt lgkmcnt(3)
; #define LAS __attribute__((address_space(3)))
; template <int pass>
; __device__ __forceinline__ void rw_item(const Params& p, int l, int seg, int h, LAS float* sm, int tid, int lane, int wave) {
;     ...
;         for (int t = 0; t < TS; ++t) {
;             const f32x4 w4 = nw4, k4 = nk4, a4 = na4, b4 = nb4, q4 = nq4; const f32x2 vv = nvv;
;             {
;                 const int tn = (t + 1 < TS) ? t + 1 : t, on = tn * 64 + kq * 4;
;                 nw4 = *(const LAS f32x4*)(bf + 1024 + on); nk4 = *(const LAS f32x4*)(bf + 2048 + on);
;                 na4 = *(const LAS f32x4*)(bf + 3072 + on); nb4 = *(const LAS f32x4*)(bf + 4096 + on);
;                 nvv = *(const LAS f32x2*)(bf + 5120 + tn * 64 + j0);
;                 if (pass == 1) nq4 = *(const LAS f32x4*)(bf + on);
;             }
;             const f32x2 vA = {vv.x, vv.x}, vB = {vv.y, vv.y};
;             f32x2 ua = b4.xy * sA[0], ub = b4.xy * sB[0];
;             ua = b4.zw * sA[1] + ua; ub = b4.zw * sB[1] + ub;
;             float uA = ua.x + ua.y, uB = ub.x + ub.y, gA = 0.f, gB = 0.f;
;             if (pass == 0) {
;                 f32x2 qa = b4.xy * pA[0], qb = b4.xy * pB[0];
;                 qa = b4.zw * pA[1] + qa; qb = b4.zw * pB[1] + qb;
;                 gA = qa.x + qa.y; gB = qb.x + qb.y;
;                 kq_sum16x4(uA, uB, gA, gB);
;             } else { uA = kq_sum<16>(uA); uB = kq_sum<16>(uB); }
;             const f32x2 uA2 = {uA, uA}, uB2 = {uB, uB};
;             { const f32x2 t0_ = k4.xy * vA - a4.xy * uA2, t1_ = k4.zw * vA - a4.zw * uA2; sA[0] = w4.xy * sA[0] + t0_; sA[1] = w4.zw * sA[1] + t1_; }
;             { const f32x2 t0_ = k4.xy * vB - a4.xy * uB2, t1_ = k4.zw * vB - a4.zw * uB2; sB[0] = w4.xy * sB[0] + t0_; sB[1] = w4.zw * sB[1] + t1_; }
;             if (pass == 0) {
;                 const f32x2 gA2 = {gA, gA}, gB2 = {gB, gB};
;                 pA[0] = w4.xy * pA[0] - a4.xy * gA2; pA[1] = w4.zw * pA[1] - a4.zw * gA2;
;                 pB[0] = w4.xy * pB[0] - a4.xy * gB2; pB[1] = w4.zw * pB[1] - a4.zw * gB2;
;             } else {
;                 f32x2 oa = q4.xy * sA[0], ob2 = q4.xy * sB[0];
;                 oa = q4.zw * sA[1] + oa; ob2 = q4.zw * sB[1] + ob2;
;                 const float oA = kq_sum<16>(oa.x + oa.y), oB = kq_sum<16>(ob2.x + ob2.y);
;                 if (kq == 0) *(LAS f32x2*)(ob + t * 64 + j0) = (f32x2){oA, oB};
;             }
;         }
	v_pk_mul_f32 v[66:67], v[40:41], v[48:49]
	v_pk_mul_f32 v[40:41], v[40:41], v[52:53]
	v_pk_fma_f32 v[66:67], v[38:39], v[46:47], v[66:67]
	v_pk_fma_f32 v[38:39], v[38:39], v[42:43], v[40:41]
	v_add_f32_e32 v40, v66, v67
	v_add_f32_e32 v39, v38, v39
	ds_read_b128 v[14:17], v97 offset:9216
	ds_read_b128 v[30:33], v97 offset:13312
	ds_read_b128 v[34:37], v97 offset:17408
	ds_read_b64 v[50:51], v98 offset:1024
	ds_read_b128 v[26:29], v97 offset:5120
	ds_read_b128 v[6:9], v97 offset:1024
	v_add_f32_dpp v38, v40, v40 quad_perm:[1,0,3,2] row_mask:0xf bank_mask:0xf bound_ctrl:1
	v_add_f32_dpp v39, v39, v39 quad_perm:[1,0,3,2] row_mask:0xf bank_mask:0xf bound_ctrl:1
	v_add_f32_dpp v100, v100, v100 quad_perm:[1,0,3,2] row_mask:0xf bank_mask:0xf bound_ctrl:1
	v_add_f32_dpp v101, v101, v101 quad_perm:[1,0,3,2] row_mask:0xf bank_mask:0xf bound_ctrl:1
	v_add_f32_dpp v38, v38, v38 quad_perm:[2,3,0,1] row_mask:0xf bank_mask:0xf bound_ctrl:1
	v_add_f32_dpp v39, v39, v39 quad_perm:[2,3,0,1] row_mask:0xf bank_mask:0xf bound_ctrl:1
	v_add_f32_dpp v100, v100, v100 quad_perm:[2,3,0,1] row_mask:0xf bank_mask:0xf bound_ctrl:1
	v_add_f32_dpp v101, v101, v101 quad_perm:[2,3,0,1] row_mask:0xf bank_mask:0xf bound_ctrl:1
	v_add_f32_dpp v38, v38, v38 row_half_mirror row_mask:0xf bank_mask:0xf bound_ctrl:1
	v_add_f32_dpp v39, v39, v39 row_half_mirror row_mask:0xf bank_mask:0xf bound_ctrl:1
	s_nop 0
	v_add_f32_dpp v38, v38, v38 row_mirror row_mask:0xf bank_mask:0xf bound_ctrl:1
	v_add_f32_dpp v66, v39, v39 row_mirror row_mask:0xf bank_mask:0xf bound_ctrl:1
	s_mov_b64 exec, vcc
	ds_write_b64 v96, v[100:101] offset:3072
	s_mov_b64 exec, -1
	v_pk_mul_f32 v[40:41], v[22:23], v[38:39] op_sel_hi:[1,0]
	v_pk_mul_f32 v[38:39], v[24:25], v[38:39] op_sel_hi:[1,0]
	v_pk_mul_f32 v[22:23], v[22:23], v[66:67] op_sel_hi:[1,0]
	s_waitcnt lgkmcnt(9)
	v_pk_fma_f32 v[40:41], v[10:11], v[44:45], v[40:41] op_sel_hi:[1,0,1] neg_lo:[0,0,1] neg_hi:[0,0,1]
	v_pk_fma_f32 v[68:69], v[12:13], v[44:45], v[38:39] op_sel_hi:[1,0,1] neg_lo:[0,0,1] neg_hi:[0,0,1]
	v_pk_fma_f32 v[10:11], v[10:11], v[44:45], v[22:23] op_sel:[0,1,0] neg_lo:[0,0,1] neg_hi:[0,0,1]
	v_pk_mul_f32 v[22:23], v[24:25], v[66:67] op_sel_hi:[1,0]
	s_waitcnt lgkmcnt(8)
	v_pk_fma_f32 v[38:39], v[18:19], v[46:47], v[40:41]
	v_pk_fma_f32 v[40:41], v[20:21], v[48:49], v[68:69]
	v_pk_fma_f32 v[12:13], v[12:13], v[44:45], v[22:23] op_sel:[0,1,0] neg_lo:[0,0,1] neg_hi:[0,0,1]
	v_pk_fma_f32 v[68:69], v[18:19], v[42:43], v[10:11]
	v_pk_fma_f32 v[52:53], v[20:21], v[52:53], v[12:13]
	s_waitcnt lgkmcnt(8)
	v_pk_mul_f32 v[10:11], v[2:3], v[38:39]
	v_pk_mul_f32 v[2:3], v[2:3], v[68:69]
	v_pk_fma_f32 v[10:11], v[4:5], v[40:41], v[10:11]
	v_pk_fma_f32 v[2:3], v[4:5], v[52:53], v[2:3]
	v_add_f32_e32 v101, v2, v3
	v_add_f32_e32 v100, v10, v11
	s_waitcnt lgkmcnt(3)
	v_pk_mul_f32 v[2:3], v[36:37], v[40:41]
	v_pk_mul_f32 v[4:5], v[36:37], v[52:53]
	v_pk_fma_f32 v[2:3], v[34:35], v[38:39], v[2:3]
	v_pk_fma_f32 v[4:5], v[34:35], v[68:69], v[4:5]
	v_add_f32_e32 v2, v2, v3
	v_add_f32_e32 v3, v4, v5
	ds_read_b128 v[18:21], v97 offset:9472
	ds_read_b128 v[42:45], v97 offset:13568
	ds_read_b128 v[46:49], v97 offset:17664
	ds_read_b64 v[66:67], v98 offset:1280
	ds_read_b128 v[22:25], v97 offset:5376
	ds_read_b128 v[10:13], v97 offset:1280
	v_add_f32_dpp v2, v2, v2 quad_perm:[1,0,3,2] row_mask:0xf bank_mask:0xf bound_ctrl:1
	v_add_f32_dpp v3, v3, v3 quad_perm:[1,0,3,2] row_mask:0xf bank_mask:0xf bound_ctrl:1
	v_add_f32_dpp v100, v100, v100 quad_perm:[1,0,3,2] row_mask:0xf bank_mask:0xf bound_ctrl:1
	v_add_f32_dpp v101, v101, v101 quad_perm:[1,0,3,2] row_mask:0xf bank_mask:0xf bound_ctrl:1
	v_add_f32_dpp v2, v2, v2 quad_perm:[2,3,0,1] row_mask:0xf bank_mask:0xf bound_ctrl:1
	v_add_f32_dpp v3, v3, v3 quad_perm:[2,3,0,1] row_mask:0xf bank_mask:0xf bound_ctrl:1
	v_add_f32_dpp v100, v100, v100 quad_perm:[2,3,0,1] row_mask:0xf bank_mask:0xf bound_ctrl:1
	v_add_f32_dpp v101, v101, v101 quad_perm:[2,3,0,1] row_mask:0xf bank_mask:0xf bound_ctrl:1
	v_add_f32_dpp v2, v2, v2 row_half_mirror row_mask:0xf bank_mask:0xf bound_ctrl:1
	v_add_f32_dpp v3, v3, v3 row_half_mirror row_mask:0xf bank_mask:0xf bound_ctrl:1
	s_nop 0
	v_add_f32_dpp v2, v2, v2 row_mirror row_mask:0xf bank_mask:0xf bound_ctrl:1
	v_add_f32_dpp v4, v3, v3 row_mirror row_mask:0xf bank_mask:0xf bound_ctrl:1
	s_mov_b64 exec, vcc
	ds_write_b64 v96, v[100:101] offset:4096
	s_mov_b64 exec, -1
	v_pk_mul_f32 v[34:35], v[30:31], v[2:3] op_sel_hi:[1,0]
	v_pk_mul_f32 v[2:3], v[32:33], v[2:3] op_sel_hi:[1,0]
	s_waitcnt lgkmcnt(9)
	v_pk_fma_f32 v[34:35], v[14:15], v[50:51], v[34:35] op_sel_hi:[1,0,1] neg_lo:[0,0,1] neg_hi:[0,0,1]
	v_pk_fma_f32 v[2:3], v[16:17], v[50:51], v[2:3] op_sel_hi:[1,0,1] neg_lo:[0,0,1] neg_hi:[0,0,1]
	s_waitcnt lgkmcnt(8)
	v_pk_fma_f32 v[70:71], v[26:27], v[38:39], v[34:35]
	v_pk_fma_f32 v[72:73], v[28:29], v[40:41], v[2:3]
	v_pk_mul_f32 v[2:3], v[30:31], v[4:5] op_sel_hi:[1,0]
	v_pk_mul_f32 v[4:5], v[32:33], v[4:5] op_sel_hi:[1,0]
	v_pk_fma_f32 v[2:3], v[14:15], v[50:51], v[2:3] op_sel:[0,1,0] neg_lo:[0,0,1] neg_hi:[0,0,1]
	v_pk_fma_f32 v[4:5], v[16:17], v[50:51], v[4:5] op_sel:[0,1,0] neg_lo:[0,0,1] neg_hi:[0,0,1]
	v_pk_fma_f32 v[14:15], v[26:27], v[68:69], v[2:3]
	v_pk_fma_f32 v[16:17], v[28:29], v[52:53], v[4:5]
	s_waitcnt lgkmcnt(8)
	v_pk_mul_f32 v[2:3], v[6:7], v[70:71]
	v_pk_mul_f32 v[4:5], v[6:7], v[14:15]
	v_pk_fma_f32 v[2:3], v[8:9], v[72:73], v[2:3]
	v_pk_fma_f32 v[4:5], v[8:9], v[16:17], v[4:5]
	v_add_f32_e32 v100, v2, v3
	v_add_f32_e32 v101, v4, v5
	s_waitcnt lgkmcnt(3)
; #define LAS __attribute__((address_space(3)))
; template <int pass>
; __device__ __forceinline__ void rw_item(const Params& p, int l, int seg, int h, LAS float* sm, int tid, int lane, int wave) {
;     ...
;         for (int t = 0; t < TS; ++t) {
;             const f32x4 w4 = nw4, k4 = nk4, a4 = na4, b4 = nb4, q4 = nq4; const f32x2 vv = nvv;
;             {
;                 const int tn = (t + 1 < TS) ? t + 1 : t, on = tn * 64 + kq * 4;
;                 nw4 = *(const LAS f32x4*)(bf + 1024 + on); nk4 = *(const LAS f32x4*)(bf + 2048 + on);
;                 na4 = *(const LAS f32x4*)(bf + 3072 + on); nb4 = *(const LAS f32x4*)(bf + 4096 + on);
;                 nvv = *(const LAS f32x2*)(bf + 5120 + tn * 64 + j0);
;                 if (pass == 1) nq4 = *(const LAS f32x4*)(bf + on);
;             }
;             const f32x2 vA = {vv.x, vv.x}, vB = {vv.y, vv.y};
;             f32x2 ua = b4.xy * sA[0], ub = b4.xy * sB[0];
;             ua = b4.zw * sA[1] + ua; ub = b4.zw * sB[1] + ub;
;             float uA = ua.x + ua.y, uB = ub.x + ub.y, gA = 0.f, gB = 0.f;
;             if (pass == 0) {
;                 f32x2 qa = b4.xy * pA[0], qb = b4.xy * pB[0];
;                 qa = b4.zw * pA[1] + qa; qb = b4.zw * pB[1] + qb;
;                 gA = qa.x + qa.y; gB = qb.x + qb.y;
;                 kq_sum16x4(uA, uB, gA, gB);
;             } else { uA = kq_sum<16>(uA); uB = kq_sum<16>(uB); }
;             const f32x2 uA2 = {uA, uA}, uB2 = {uB, uB};
;             { const f32x2 t0_ = k4.xy * vA - a4.xy * uA2, t1_ = k4.zw * vA - a4.zw * uA2; sA[0] = w4.xy * sA[0] + t0_; sA[1] = w4.zw * sA[1] + t1_; }
;             { const f32x2 t0_ = k4.xy * vB - a4.xy * uB2, t1_ = k4.zw * vB - a4.zw * uB2; sB[0] = w4.xy * sB[0] + t0_; sB[1] = w4.zw * sB[1] + t1_; }
;             if (pass == 0) {
;                 const f32x2 gA2 = {gA, gA}, gB2 = {gB, gB};
;                 pA[0] = w4.xy * pA[0] - a4.xy * gA2; pA[1] = w4.zw * pA[1] - a4.zw * gA2;
;                 pB[0] = w4.xy * pB[0] - a4.xy * gB2; pB[1] = w4.zw * pB[1] - a4.zw * gB2;
;             } else {
;                 f32x2 oa = q4.xy * sA[0], ob2 = q4.xy * sB[0];
;                 oa = q4.zw * sA[1] + oa; ob2 = q4.zw * sB[1] + ob2;
;                 const float oA = kq_sum<16>(oa.x + oa.y), oB = kq_sum<16>(ob2.x + ob2.y);
;                 if (kq == 0) *(LAS f32x2*)(ob + t * 64 + j0) = (f32x2){oA, oB};
;             }
;         }
	v_pk_mul_f32 v[26:27], v[48:49], v[72:73]
	v_pk_mul_f32 v[28:29], v[48:49], v[16:17]
	v_pk_fma_f32 v[26:27], v[46:47], v[70:71], v[26:27]
	v_pk_fma_f32 v[28:29], v[46:47], v[14:15], v[28:29]
	v_add_f32_e32 v26, v26, v27
	v_add_f32_e32 v27, v28, v29
	ds_read_b128 v[2:5], v97 offset:9728
	ds_read_b128 v[38:41], v97 offset:13824
	ds_read_b128 v[6:9], v97 offset:17920
	ds_read_b64 v[52:53], v98 offset:1536
	ds_read_b128 v[34:37], v97 offset:5632
	ds_read_b128 v[30:33], v97 offset:1536
	v_add_f32_dpp v26, v26, v26 quad_perm:[1,0,3,2] row_mask:0xf bank_mask:0xf bound_ctrl:1
	v_add_f32_dpp v27, v27, v27 quad_perm:[1,0,3,2] row_mask:0xf bank_mask:0xf bound_ctrl:1
	v_add_f32_dpp v100, v100, v100 quad_perm:[1,0,3,2] row_mask:0xf bank_mask:0xf bound_ctrl:1
	v_add_f32_dpp v101, v101, v101 quad_perm:[1,0,3,2] row_mask:0xf bank_mask:0xf bound_ctrl:1
	v_add_f32_dpp v26, v26, v26 quad_perm:[2,3,0,1] row_mask:0xf bank_mask:0xf bound_ctrl:1
	v_add_f32_dpp v27, v27, v27 quad_perm:[2,3,0,1] row_mask:0xf bank_mask:0xf bound_ctrl:1
	v_add_f32_dpp v100, v100, v100 quad_perm:[2,3,0,1] row_mask:0xf bank_mask:0xf bound_ctrl:1
	v_add_f32_dpp v101, v101, v101 quad_perm:[2,3,0,1] row_mask:0xf bank_mask:0xf bound_ctrl:1
	v_add_f32_dpp v26, v26, v26 row_half_mirror row_mask:0xf bank_mask:0xf bound_ctrl:1
	v_add_f32_dpp v27, v27, v27 row_half_mirror row_mask:0xf bank_mask:0xf bound_ctrl:1
	s_nop 0
	v_add_f32_dpp v26, v26, v26 row_mirror row_mask:0xf bank_mask:0xf bound_ctrl:1
	v_add_f32_dpp v28, v27, v27 row_mirror row_mask:0xf bank_mask:0xf bound_ctrl:1
	s_mov_b64 exec, vcc
	ds_write_b64 v96, v[100:101] offset:5120
	s_mov_b64 exec, -1
	v_pk_mul_f32 v[46:47], v[42:43], v[26:27] op_sel_hi:[1,0]
	v_pk_mul_f32 v[26:27], v[44:45], v[26:27] op_sel_hi:[1,0]
	s_waitcnt lgkmcnt(9)
	v_pk_fma_f32 v[46:47], v[18:19], v[66:67], v[46:47] op_sel_hi:[1,0,1] neg_lo:[0,0,1] neg_hi:[0,0,1]
	v_pk_fma_f32 v[26:27], v[20:21], v[66:67], v[26:27] op_sel_hi:[1,0,1] neg_lo:[0,0,1] neg_hi:[0,0,1]
	s_waitcnt lgkmcnt(8)
	v_pk_fma_f32 v[46:47], v[22:23], v[70:71], v[46:47]
	v_pk_fma_f32 v[48:49], v[24:25], v[72:73], v[26:27]
	v_pk_mul_f32 v[26:27], v[42:43], v[28:29] op_sel_hi:[1,0]
	s_nop 0
	v_pk_fma_f32 v[18:19], v[18:19], v[66:67], v[26:27] op_sel:[0,1,0] neg_lo:[0,0,1] neg_hi:[0,0,1]
	v_pk_mul_f32 v[26:27], v[44:45], v[28:29] op_sel_hi:[1,0]
	v_pk_fma_f32 v[42:43], v[22:23], v[14:15], v[18:19]
	v_pk_fma_f32 v[20:21], v[20:21], v[66:67], v[26:27] op_sel:[0,1,0] neg_lo:[0,0,1] neg_hi:[0,0,1]
	s_waitcnt lgkmcnt(8)
	v_pk_mul_f32 v[14:15], v[10:11], v[46:47]
	v_pk_fma_f32 v[44:45], v[24:25], v[16:17], v[20:21]
	v_pk_mul_f32 v[10:11], v[10:11], v[42:43]
	v_pk_fma_f32 v[14:15], v[12:13], v[48:49], v[14:15]
	v_pk_fma_f32 v[10:11], v[12:13], v[44:45], v[10:11]
	v_add_f32_e32 v101, v10, v11
	v_add_f32_e32 v100, v14, v15
	s_waitcnt lgkmcnt(3)
	v_pk_mul_f32 v[66:67], v[8:9], v[48:49]
	v_pk_mul_f32 v[8:9], v[8:9], v[44:45]
	v_pk_fma_f32 v[66:67], v[6:7], v[46:47], v[66:67]
	v_pk_fma_f32 v[6:7], v[6:7], v[42:43], v[8:9]
	v_add_f32_e32 v8, v66, v67
	v_add_f32_e32 v7, v6, v7
	s_cmpk_lg_i32 s38, 0x800
	v_add_f32_dpp v6, v8, v8 quad_perm:[1,0,3,2] row_mask:0xf bank_mask:0xf bound_ctrl:1
	v_add_f32_dpp v7, v7, v7 quad_perm:[1,0,3,2] row_mask:0xf bank_mask:0xf bound_ctrl:1
	v_add_f32_dpp v100, v100, v100 quad_perm:[1,0,3,2] row_mask:0xf bank_mask:0xf bound_ctrl:1
	v_add_f32_dpp v101, v101, v101 quad_perm:[1,0,3,2] row_mask:0xf bank_mask:0xf bound_ctrl:1
	s_cselect_b32 s0, s37, 0x3c0
	v_add_f32_dpp v6, v6, v6 quad_perm:[2,3,0,1] row_mask:0xf bank_mask:0xf bound_ctrl:1
	v_add_f32_dpp v7, v7, v7 quad_perm:[2,3,0,1] row_mask:0xf bank_mask:0xf bound_ctrl:1
	v_add_f32_dpp v100, v100, v100 quad_perm:[2,3,0,1] row_mask:0xf bank_mask:0xf bound_ctrl:1
	v_add_f32_dpp v101, v101, v101 quad_perm:[2,3,0,1] row_mask:0xf bank_mask:0xf bound_ctrl:1
	v_or_b32_e32 v10, s0, v0
	v_add_f32_dpp v6, v6, v6 row_half_mirror row_mask:0xf bank_mask:0xf bound_ctrl:1
	v_add_f32_dpp v7, v7, v7 row_half_mirror row_mask:0xf bank_mask:0xf bound_ctrl:1
	s_nop 0
	v_lshl_add_u32 v22, v10, 2, s5
	v_add_f32_dpp v6, v6, v6 row_mirror row_mask:0xf bank_mask:0xf bound_ctrl:1
	v_add_f32_dpp v66, v7, v7 row_mirror row_mask:0xf bank_mask:0xf bound_ctrl:1
	s_mov_b64 exec, vcc
	ds_write_b64 v96, v[100:101] offset:6144
	s_mov_b64 exec, -1
	v_pk_mul_f32 v[8:9], v[38:39], v[6:7] op_sel_hi:[1,0]
	v_pk_mul_f32 v[38:39], v[38:39], v[66:67] op_sel_hi:[1,0]
	s_waitcnt lgkmcnt(3)
	v_pk_fma_f32 v[8:9], v[2:3], v[52:53], v[8:9] op_sel_hi:[1,0,1] neg_lo:[0,0,1] neg_hi:[0,0,1]
	v_pk_mul_f32 v[6:7], v[40:41], v[6:7] op_sel_hi:[1,0]
	v_pk_fma_f32 v[2:3], v[2:3], v[52:53], v[38:39] op_sel:[0,1,0] neg_lo:[0,0,1] neg_hi:[0,0,1]
	v_pk_mul_f32 v[38:39], v[40:41], v[66:67] op_sel_hi:[1,0]
	v_pk_fma_f32 v[68:69], v[4:5], v[52:53], v[6:7] op_sel_hi:[1,0,1] neg_lo:[0,0,1] neg_hi:[0,0,1]
	s_waitcnt lgkmcnt(2)
	v_pk_fma_f32 v[6:7], v[34:35], v[46:47], v[8:9]
	v_pk_fma_f32 v[4:5], v[4:5], v[52:53], v[38:39] op_sel:[0,1,0] neg_lo:[0,0,1] neg_hi:[0,0,1]
	v_pk_fma_f32 v[2:3], v[34:35], v[42:43], v[2:3]
	v_pk_fma_f32 v[8:9], v[36:37], v[48:49], v[68:69]
	v_pk_fma_f32 v[4:5], v[36:37], v[44:45], v[4:5]
	s_waitcnt lgkmcnt(2)
	v_pk_mul_f32 v[34:35], v[30:31], v[6:7]
	v_pk_mul_f32 v[30:31], v[30:31], v[2:3]
	v_pk_fma_f32 v[34:35], v[32:33], v[8:9], v[34:35]
	v_pk_fma_f32 v[30:31], v[32:33], v[4:5], v[30:31]
	v_add_f32_e32 v31, v30, v31
	v_add_f32_e32 v30, v34, v35
	v_lshl_add_u32 v10, s0, 2, v93
	ds_read_b128 v[14:17], v22 offset:8192
	ds_read_b128 v[18:21], v22 offset:12288
	ds_read_b128 v[26:29], v22 offset:16384
	ds_read_b64 v[50:51], v10 offset:20480
	ds_read_b128 v[10:13], v22 offset:4096
	ds_read_b128 v[22:25], v22
	v_add_f32_dpp v30, v30, v30 quad_perm:[1,0,3,2] row_mask:0xf bank_mask:0xf bound_ctrl:1
	v_add_f32_dpp v31, v31, v31 quad_perm:[1,0,3,2] row_mask:0xf bank_mask:0xf bound_ctrl:1
	s_nop 0
	v_add_f32_dpp v30, v30, v30 quad_perm:[2,3,0,1] row_mask:0xf bank_mask:0xf bound_ctrl:1
	v_add_f32_dpp v31, v31, v31 quad_perm:[2,3,0,1] row_mask:0xf bank_mask:0xf bound_ctrl:1
	s_and_saveexec_b64 s[0:1], vcc
	s_cbranch_execz .LBB0_456
	ds_write_b64 v96, v[30:31] offset:7168
	s_branch .LBB0_456

; template <class Epi, class Sched>
; __device__ __forceinline__ void gemm_phase(PG8_LAS unsigned char* lds, const Gemm g, const Sched& S, const Epi& E) {
;     ...
;         const bool has_next = S.next(ui + 1, nxt);
;         const char* nA = has_next ? (const char*)g.A + (size_t)nxt.pm * tstep : cA; const char* nB = has_next ? (const char*)g.Bt + (size_t)nxt.pn * tstep : cB;
;         for (int t = 0; t < nt; t += 2) {
;             const bool last = (t == nt - 2);
;             const char* a1 = cA + (size_t)(t + 1) * kstep;
;             const char* a2 = last ? nA : cA + (size_t)(t + 2) * kstep; const char* b2 = last ? nB : cB + (size_t)(t + 2) * kstep;
;     ...
;         for (int a = 0; a < 2; ++a)
; #pragma unroll
;             for (int b = 0; b < 2; ++b)
; #pragma unroll
;                 for (int m = 0; m < 4; ++m)
; #pragma unroll
;                     for (int n = 0; n < 2; ++n) acc[a][b][m][n] = (f32x4){0.f, 0.f, 0.f, 0.f};
.LBB0_1070:
	v_mov_b64_e32 v[2:3], 0x440
	s_ashr_i32 s13, s12, 31
	v_cmp_lt_i64_e32 vcc, s[14:15], v[2:3]
	s_lshl_b64 s[14:15], s[12:13], 19
	s_add_u32 s14, s24, s14
	s_addc_u32 s15, s25, s15
	s_and_b64 s[16:17], vcc, exec
	s_cselect_b32 s13, s15, s19
	s_cselect_b32 s40, s14, s18
	s_ashr_i32 s11, s10, 31
	s_lshl_b64 s[16:17], s[10:11], 19
	s_add_u32 s16, s26, s16
	s_addc_u32 s17, s27, s17
	s_and_b64 s[22:23], vcc, exec
	s_cselect_b32 s11, s17, s21
	s_cselect_b32 s41, s16, s20
	s_add_u32 s18, s18, 0x40080
	s_addc_u32 s19, s19, 0
	s_add_u32 s44, s20, 0x100
	v_mov_b32_e32 v2, 0
	s_addc_u32 s45, s21, 0
	s_mov_b32 s50, -2
	v_mov_b32_e32 v3, v2
	v_mov_b64_e32 v[4:5], 0
	v_mov_b64_e32 v[6:7], 0
	v_mov_b64_e32 v[8:9], 0
	v_mov_b64_e32 v[14:15], 0
	v_mov_b64_e32 v[16:17], 0
	v_mov_b64_e32 v[22:23], 0
	v_mov_b64_e32 v[24:25], 0
	v_mov_b64_e32 v[30:31], 0
	s_waitcnt lgkmcnt(0)
	v_mov_b64_e32 v[32:33], 0
	v_mov_b64_e32 v[38:39], 0
	v_mov_b64_e32 v[40:41], 0
	v_mov_b64_e32 v[46:47], 0
	v_mov_b64_e32 v[48:49], 0
	v_mov_b64_e32 v[54:55], 0
	v_mov_b64_e32 v[56:57], 0
	v_mov_b64_e32 v[10:11], 0
	v_mov_b64_e32 v[12:13], 0
	v_mov_b64_e32 v[18:19], 0
	v_mov_b64_e32 v[20:21], 0
	v_mov_b64_e32 v[26:27], 0
	v_mov_b64_e32 v[28:29], 0
	v_mov_b64_e32 v[34:35], 0
	v_mov_b64_e32 v[36:37], 0
	v_mov_b64_e32 v[42:43], 0
	v_mov_b64_e32 v[44:45], 0
	v_mov_b64_e32 v[50:51], 0
	v_mov_b64_e32 v[52:53], 0
	v_mov_b64_e32 v[58:59], 0
	v_mov_b64_e32 v[60:61], 0
	v_mov_b64_e32 v[62:63], 0
	v_mov_b64_e32 v[64:65], 0
	v_mov_b64_e32 v[66:67], 0
	v_mov_b64_e32 v[68:69], 0
	v_mov_b64_e32 v[70:71], 0
	v_mov_b64_e32 v[72:73], 0
	v_mov_b64_e32 v[74:75], 0
	v_mov_b64_e32 v[76:77], 0
	v_mov_b64_e32 v[82:83], 0
	v_mov_b64_e32 v[84:85], 0
	v_mov_b64_e32 v[90:91], 0
	v_mov_b64_e32 v[92:93], 0
	v_mov_b64_e32 v[98:99], 0
	v_mov_b64_e32 v[100:101], 0
	v_mov_b64_e32 v[106:107], 0
	v_mov_b64_e32 v[108:109], 0
	v_mov_b64_e32 v[114:115], 0
	v_mov_b64_e32 v[116:117], 0
	v_mov_b64_e32 v[78:79], 0
	v_mov_b64_e32 v[80:81], 0
	v_mov_b64_e32 v[86:87], 0
	v_mov_b64_e32 v[88:89], 0
	v_mov_b64_e32 v[94:95], 0
	v_mov_b64_e32 v[96:97], 0
	v_mov_b64_e32 v[102:103], 0
	v_mov_b64_e32 v[104:105], 0
	v_mov_b64_e32 v[110:111], 0
	v_mov_b64_e32 v[112:113], 0
	v_mov_b64_e32 v[118:119], 0
	v_mov_b64_e32 v[120:121], 0
	v_mov_b64_e32 v[122:123], 0
	v_mov_b64_e32 v[124:125], 0
	v_mov_b64_e32 v[126:127], 0
	v_mov_b64_e32 v[128:129], 0

; template <class Epi, class Sched>
; __device__ __forceinline__ void gemm_phase(PG8_LAS unsigned char* lds, const Gemm g, const Sched& S, const Epi& E) {
;     ...
; #pragma unroll
;         for (int a = 0; a < 2; ++a)
; #pragma unroll
;             for (int b = 0; b < 2; ++b)
; #pragma unroll
;                 for (int m = 0; m < 4; ++m)
; #pragma unroll
;                     for (int n = 0; n < 2; ++n) acc[a][b][m][n] = (f32x4){0.f, 0.f, 0.f, 0.f};
;         cur = nxt; cA = nA; cB = nB; ++ui;
.LBB0_1105:
	s_add_u32 s10, s10, 0x80
	s_addc_u32 s11, s11, 0
	s_add_u32 s39, s12, 0x100
	v_mov_b32_e32 v2, 0
	s_addc_u32 s40, s13, 0
	s_mov_b32 s12, 0
	v_mov_b32_e32 v3, v2
	v_mov_b64_e32 v[4:5], 0
	v_mov_b64_e32 v[6:7], 0
	v_mov_b64_e32 v[8:9], 0
	v_mov_b64_e32 v[18:19], 0
	v_mov_b64_e32 v[20:21], 0
	v_mov_b64_e32 v[22:23], 0
	v_mov_b64_e32 v[24:25], 0
	v_mov_b64_e32 v[34:35], 0
	v_mov_b64_e32 v[36:37], 0
	v_mov_b64_e32 v[38:39], 0
	v_mov_b64_e32 v[40:41], 0
	v_mov_b64_e32 v[50:51], 0
	v_mov_b64_e32 v[52:53], 0
	v_mov_b64_e32 v[54:55], 0
	v_mov_b64_e32 v[56:57], 0
	v_mov_b64_e32 v[10:11], 0
	v_mov_b64_e32 v[12:13], 0
	v_mov_b64_e32 v[14:15], 0
	v_mov_b64_e32 v[16:17], 0
	v_mov_b64_e32 v[26:27], 0
	v_mov_b64_e32 v[28:29], 0
	v_mov_b64_e32 v[30:31], 0
	v_mov_b64_e32 v[32:33], 0
	v_mov_b64_e32 v[42:43], 0
	v_mov_b64_e32 v[44:45], 0
	v_mov_b64_e32 v[46:47], 0
	v_mov_b64_e32 v[48:49], 0
	v_mov_b64_e32 v[58:59], 0
	v_mov_b64_e32 v[60:61], 0
	v_mov_b64_e32 v[62:63], 0
	v_mov_b64_e32 v[64:65], 0
	v_mov_b64_e32 v[66:67], 0
	v_mov_b64_e32 v[68:69], 0
	v_mov_b64_e32 v[70:71], 0
	v_mov_b64_e32 v[72:73], 0
	v_mov_b64_e32 v[82:83], 0
	v_mov_b64_e32 v[84:85], 0
	v_mov_b64_e32 v[86:87], 0
	v_mov_b64_e32 v[88:89], 0
	v_mov_b64_e32 v[98:99], 0
	v_mov_b64_e32 v[100:101], 0
	v_mov_b64_e32 v[102:103], 0
	v_mov_b64_e32 v[104:105], 0
	v_mov_b64_e32 v[114:115], 0
	v_mov_b64_e32 v[116:117], 0
	v_mov_b64_e32 v[118:119], 0
	v_mov_b64_e32 v[120:121], 0
	v_mov_b64_e32 v[74:75], 0
	v_mov_b64_e32 v[76:77], 0
	v_mov_b64_e32 v[78:79], 0
	v_mov_b64_e32 v[80:81], 0
	v_mov_b64_e32 v[90:91], 0
	v_mov_b64_e32 v[92:93], 0
	v_mov_b64_e32 v[94:95], 0
	v_mov_b64_e32 v[96:97], 0
	v_mov_b64_e32 v[106:107], 0
	v_mov_b64_e32 v[108:109], 0
	v_mov_b64_e32 v[110:111], 0
	v_mov_b64_e32 v[112:113], 0
	v_mov_b64_e32 v[122:123], 0
	v_mov_b64_e32 v[124:125], 0
	v_mov_b64_e32 v[126:127], 0
	v_mov_b64_e32 v[128:129], 0

; template <class Epi, class Sched>
; __device__ __forceinline__ void gemm_phase(PG8_LAS unsigned char* lds, const Gemm g, const Sched& S, const Epi& E) {
;     ...
;         const bool has_next = S.next(ui + 1, nxt);
;         const char* nA = has_next ? (const char*)g.A + (size_t)nxt.pm * tstep : cA; const char* nB = has_next ? (const char*)g.Bt + (size_t)nxt.pn * tstep : cB;
;     ...
; #pragma unroll
;         for (int a = 0; a < 2; ++a)
; #pragma unroll
;             for (int b = 0; b < 2; ++b)
; #pragma unroll
;                 for (int m = 0; m < 4; ++m)
; #pragma unroll
;                     for (int n = 0; n < 2; ++n) acc[a][b][m][n] = (f32x4){0.f, 0.f, 0.f, 0.f};
;         cur = nxt; cA = nA; cB = nB; ++ui;
.LBB0_1128:
	s_ashr_i32 s9, s8, 31
	v_cmp_lt_i64_e32 vcc, s[10:11], v[132:133]
	s_lshl_b64 s[10:11], s[8:9], 19
	s_add_u32 s10, s20, s10
	s_addc_u32 s11, s21, s11
	s_and_b64 s[12:13], vcc, exec
	s_cselect_b32 s9, s11, s15
	s_cselect_b32 s36, s10, s14
	s_ashr_i32 s7, s6, 31
	s_lshl_b64 s[12:13], s[6:7], 19
	s_add_u32 s12, s22, s12
	s_addc_u32 s13, s23, s13
	s_and_b64 s[18:19], vcc, exec
	s_cselect_b32 s7, s13, s17
	s_cselect_b32 s37, s12, s16
	s_add_u32 s14, s14, 0x40080
	s_addc_u32 s15, s15, 0
	s_add_u32 s38, s16, 0x100
	v_mov_b32_e32 v2, 0
	s_addc_u32 s39, s17, 0
	s_mov_b32 s40, -2
	v_mov_b32_e32 v3, v2
	v_mov_b64_e32 v[4:5], 0
	v_mov_b64_e32 v[10:11], 0
	v_mov_b64_e32 v[12:13], 0
	v_mov_b64_e32 v[18:19], 0
	v_mov_b64_e32 v[20:21], 0
	v_mov_b64_e32 v[26:27], 0
	v_mov_b64_e32 v[28:29], 0
	v_mov_b64_e32 v[34:35], 0
	v_mov_b64_e32 v[36:37], 0
	v_mov_b64_e32 v[42:43], 0
	v_mov_b64_e32 v[44:45], 0
	v_mov_b64_e32 v[50:51], 0
	v_mov_b64_e32 v[52:53], 0
	v_mov_b64_e32 v[58:59], 0
	v_mov_b64_e32 v[60:61], 0
	v_mov_b64_e32 v[6:7], 0
	v_mov_b64_e32 v[8:9], 0
	v_mov_b64_e32 v[14:15], 0
	v_mov_b64_e32 v[16:17], 0
	v_mov_b64_e32 v[22:23], 0
	v_mov_b64_e32 v[24:25], 0
	v_mov_b64_e32 v[30:31], 0
	v_mov_b64_e32 v[32:33], 0
	v_mov_b64_e32 v[38:39], 0
	v_mov_b64_e32 v[40:41], 0
	v_mov_b64_e32 v[46:47], 0
	v_mov_b64_e32 v[48:49], 0
	v_mov_b64_e32 v[54:55], 0
	v_mov_b64_e32 v[56:57], 0
	v_mov_b64_e32 v[62:63], 0
	v_mov_b64_e32 v[64:65], 0
	v_mov_b64_e32 v[66:67], 0
	v_mov_b64_e32 v[68:69], 0
	v_mov_b64_e32 v[74:75], 0
	v_mov_b64_e32 v[76:77], 0
	v_mov_b64_e32 v[82:83], 0
	v_mov_b64_e32 v[84:85], 0
	v_mov_b64_e32 v[90:91], 0
	v_mov_b64_e32 v[92:93], 0
	v_mov_b64_e32 v[98:99], 0
	v_mov_b64_e32 v[100:101], 0
	v_mov_b64_e32 v[106:107], 0
	v_mov_b64_e32 v[108:109], 0
	v_mov_b64_e32 v[114:115], 0
	v_mov_b64_e32 v[116:117], 0
	v_mov_b64_e32 v[122:123], 0
	v_mov_b64_e32 v[124:125], 0
	v_mov_b64_e32 v[70:71], 0
	v_mov_b64_e32 v[72:73], 0
	v_mov_b64_e32 v[78:79], 0
	v_mov_b64_e32 v[80:81], 0
	v_mov_b64_e32 v[86:87], 0
	v_mov_b64_e32 v[88:89], 0
	v_mov_b64_e32 v[94:95], 0
	v_mov_b64_e32 v[96:97], 0
	v_mov_b64_e32 v[102:103], 0
	v_mov_b64_e32 v[104:105], 0
	v_mov_b64_e32 v[110:111], 0
	v_mov_b64_e32 v[112:113], 0
	v_mov_b64_e32 v[118:119], 0
	v_mov_b64_e32 v[120:121], 0
	v_mov_b64_e32 v[126:127], 0
	v_mov_b64_e32 v[128:129], 0
